# P4 tiles: first K iteration peeled with SrcC=0, accumulator clears removed (same as P1)
# baseline (speedup 1.0000x reference)
; #define PG8_STAGE(bufoff, gbase, voff) do { _Pragma("unroll") for (int _i = 0; _i < 2; ++_i) \
;         __builtin_amdgcn_global_load_lds((const unsigned*)((const char*)(gbase) + (voff)[_i]), (LAS unsigned*)(lds + (bufoff) + ldsw + _i * 8192), 16, 0, 0); } while (0)
; #define PG8_LDA(dst, b, h) do { _Pragma("unroll") for (int m = 0; m < 4; ++m) _Pragma("unroll") for (int k = 0; k < 2; ++k) dst[m][k] = *(const LAS bf16x8*)(lds + PG8_SA(b, h) + aoff + m * 2048 + k * 1024); } while (0)
; #define PG8_LDB(dst, b, h) do { _Pragma("unroll") for (int n = 0; n < 2; ++n) _Pragma("unroll") for (int k = 0; k < 2; ++k) dst[n][k] = *(const LAS bf16x8*)(lds + PG8_SB(b, h) + boff + n * 2048 + k * 1024); } while (0)
; #define PG8_WAIT_V(n) asm volatile("s_waitcnt vmcnt(" #n ")" ::: "memory")
; #define PG8_WAIT_L(n) asm volatile("s_waitcnt lgkmcnt(" #n ")" ::: "memory")
; #define PG8_BAR __builtin_amdgcn_s_barrier()
; #define PG8_SCHED __builtin_amdgcn_sched_barrier(0)
; template <class Epi, class Sched>
; __device__ __forceinline__ void gemm_phase(LAS unsigned char* lds, const Gemm g, const Sched& S, const Epi& E) {
;     ...
;     for (;;) {
;         const bool has_next = S.next(ui + 1, nxt);
;         const char* nA = has_next ? (const char*)g.A + (size_t)nxt.b * g.abs * 2 + (size_t)nxt.pm * tstepA : cA;
;         const char* nB = has_next ? (const char*)g.Bt + (size_t)nxt.b * g.bbs * 2 + (size_t)nxt.pn * tstepB : cB;
;         for (int t = 0; t < nt; t += 2) {
;             const bool last = (t == nt - 2);
;             const char* a1 = cA + (size_t)(t + 1) * kstep;
;             const char* a2 = last ? nA : cA + (size_t)(t + 2) * kstep; const char* b2 = last ? nB : cB + (size_t)(t + 2) * kstep;
;             const char* a3 = a2 + kstep; const char* b3 = b2 + kstep;
;             PG8_LDB(B0, 0, 0); PG8_LDB(B1, 0, 1); PG8_SCHED; PG8_LDA(At, 0, 0); PG8_STAGE(PG8_SA(1, 1), a1 + hstepA, voffA);
;             PG8_WAIT_V(8); PG8_WAIT_L(0); PG8_BAR; PG8_MMA(0, 0, At, B0); PG8_MMA(0, 1, At, B1); PG8_BAR; PG8_SCHED;
;             PG8_LDA(At, 0, 1); PG8_STAGE(PG8_SB(0, 0), b2, voffB); PG8_STAGE(PG8_SB(0, 1), b2 + hstepB, voffB); PG8_STAGE(PG8_SA(0, 0), a2, voffA);
;             PG8_WAIT_V(8); PG8_WAIT_L(0); PG8_BAR; PG8_MMA(1, 0, At, B0); PG8_MMA(1, 1, At, B1); PG8_BAR; PG8_SCHED;
.LBB0_509:
	s_ashr_i32 s19, s18, 31
	s_lshl_b64 s[14:15], s[18:19], 19
	s_add_u32 s20, s9, s14
	s_addc_u32 s21, s3, s15
	s_and_b64 s[14:15], s[38:39], exec
	s_cselect_b32 s14, s21, s25
	s_cselect_b32 s15, s20, s24
	s_ashr_i32 s17, s16, 31
	s_lshl_b64 s[22:23], s[16:17], 19
	s_add_u32 s22, s30, s22
	s_addc_u32 s23, s31, s23
	s_and_b64 s[36:37], s[38:39], exec
	s_cselect_b32 s17, s23, s27
	s_cselect_b32 s19, s22, s26
	s_add_u32 s24, s24, 0x40080
	s_addc_u32 s25, s25, 0
	s_add_u32 s49, s26, 0x100
	s_addc_u32 s50, s27, 0
	s_mov_b32 s51, -2
	s_waitcnt lgkmcnt(0)
	s_cmp_eq_u32 s61, 0
	s_cbranch_scc1 .Lp4_nobar
	s_mov_b32 s61, 0
	s_barrier
.Lp4_nobar:
	s_add_u32 s26, s24, 0xfffc0080
	s_addc_u32 s27, s25, -1
	s_add_i32 s52, 0, 0x10000
	s_cmp_eq_u32 s51, 12
	s_cselect_b32 s37, s14, s27
	s_cselect_b32 s36, s15, s26
	s_cselect_b32 s27, s17, s50
	s_cselect_b32 s26, s19, s49
	s_add_i32 s54, 0, 0x14000
	v_add_u32_e32 v140, s52, v178
	v_add_u32_e32 v168, s54, v178
	ds_read_b128 v[128:131], v140
	ds_read_b128 v[132:135], v140 offset:1024
	ds_read_b128 v[136:139], v140 offset:2048
	ds_read_b128 v[140:143], v140 offset:3072
	ds_read_b128 v[144:147], v168
	ds_read_b128 v[148:151], v168 offset:1024
	ds_read_b128 v[152:155], v168 offset:2048
	ds_read_b128 v[168:171], v168 offset:3072
	s_add_i32 m0, s6, 0xc000
	ds_read_b128 v[172:175], v179
	ds_read_b128 v[180:183], v179 offset:1024
	ds_read_b128 v[184:187], v179 offset:2048
	ds_read_b128 v[188:191], v179 offset:3072
	ds_read_b128 v[192:195], v179 offset:4096
	ds_read_b128 v[196:199], v179 offset:5120
	ds_read_b128 v[200:203], v179 offset:6144
	ds_read_b128 v[204:207], v179 offset:7168
	global_load_lds_dwordx4 v164, s[24:25]
	s_add_i32 m0, s6, 0xe000
	s_nop 0
	global_load_lds_dwordx4 v166, s[24:25]
	s_waitcnt vmcnt(8)
	s_waitcnt lgkmcnt(0)
	s_barrier
	s_setprio 1
	s_waitcnt lgkmcnt(0)
	v_mfma_f32_16x16x32_bf16 v[124:127], v[128:131], v[172:175], 0
	v_mfma_f32_16x16x32_bf16 v[120:123], v[136:139], v[172:175], 0
	v_mfma_f32_16x16x32_bf16 v[112:115], v[128:131], v[184:187], 0
	v_mfma_f32_16x16x32_bf16 v[104:107], v[136:139], v[184:187], 0
	v_mfma_f32_16x16x32_bf16 v[96:99], v[128:131], v[192:195], 0
	v_mfma_f32_16x16x32_bf16 v[88:91], v[136:139], v[192:195], 0
	v_mfma_f32_16x16x32_bf16 v[80:83], v[128:131], v[200:203], 0
	v_mfma_f32_16x16x32_bf16 v[72:75], v[136:139], v[200:203], 0
	v_mfma_f32_16x16x32_bf16 v[124:127], v[132:135], v[180:183], v[124:127]
	v_mfma_f32_16x16x32_bf16 v[120:123], v[140:143], v[180:183], v[120:123]
	v_mfma_f32_16x16x32_bf16 v[112:115], v[132:135], v[188:191], v[112:115]
	v_mfma_f32_16x16x32_bf16 v[104:107], v[140:143], v[188:191], v[104:107]
	v_mfma_f32_16x16x32_bf16 v[96:99], v[132:135], v[196:199], v[96:99]
	v_mfma_f32_16x16x32_bf16 v[88:91], v[140:143], v[196:199], v[88:91]
	v_mfma_f32_16x16x32_bf16 v[80:83], v[132:135], v[204:207], v[80:83]
	v_mfma_f32_16x16x32_bf16 v[72:75], v[140:143], v[204:207], v[72:75]
	s_setprio 0
	s_setprio 1
	v_mfma_f32_16x16x32_bf16 v[116:119], v[144:147], v[172:175], 0
	v_mfma_f32_16x16x32_bf16 v[108:111], v[152:155], v[172:175], 0
	v_mfma_f32_16x16x32_bf16 v[100:103], v[144:147], v[184:187], 0
	v_mfma_f32_16x16x32_bf16 v[92:95], v[152:155], v[184:187], 0
	v_mfma_f32_16x16x32_bf16 v[84:87], v[144:147], v[192:195], 0
	v_mfma_f32_16x16x32_bf16 v[76:79], v[152:155], v[192:195], 0
	v_mfma_f32_16x16x32_bf16 v[68:71], v[144:147], v[200:203], 0
	v_mfma_f32_16x16x32_bf16 v[64:67], v[152:155], v[200:203], 0
	v_mfma_f32_16x16x32_bf16 v[116:119], v[148:151], v[180:183], v[116:119]
	v_mfma_f32_16x16x32_bf16 v[108:111], v[168:171], v[180:183], v[108:111]
	v_mfma_f32_16x16x32_bf16 v[100:103], v[148:151], v[188:191], v[100:103]
	v_mfma_f32_16x16x32_bf16 v[92:95], v[168:171], v[188:191], v[92:95]
	v_mfma_f32_16x16x32_bf16 v[84:87], v[148:151], v[196:199], v[84:87]
	v_mfma_f32_16x16x32_bf16 v[76:79], v[168:171], v[196:199], v[76:79]
	v_mfma_f32_16x16x32_bf16 v[68:71], v[148:151], v[204:207], v[68:71]
	v_mfma_f32_16x16x32_bf16 v[64:67], v[168:171], v[204:207], v[64:67]
	s_setprio 0
	s_barrier
	s_add_i32 s52, s52, s2
	s_mov_b32 m0, s52
	ds_read_b128 v[172:175], v179 offset:16384
	ds_read_b128 v[180:183], v179 offset:17408
	ds_read_b128 v[184:187], v179 offset:18432
	ds_read_b128 v[188:191], v179 offset:19456
	ds_read_b128 v[192:195], v179 offset:20480
	ds_read_b128 v[196:199], v179 offset:21504
	ds_read_b128 v[200:203], v179 offset:22528
	ds_read_b128 v[204:207], v179 offset:23552
	global_load_lds_dwordx4 v160, s[26:27]
	s_add_i32 m0, s52, 0x2000
	s_add_u32 s52, s26, 0x40000
	s_addc_u32 s53, s27, 0
	s_add_i32 s54, s54, s2
	global_load_lds_dwordx4 v156, s[26:27]
	s_mov_b32 m0, s54
	s_nop 0
	global_load_lds_dwordx4 v160, s[52:53]
	s_add_i32 m0, s54, 0x2000
	s_nop 0
	global_load_lds_dwordx4 v156, s[52:53]
	s_mov_b32 m0, s6
	s_nop 0
	global_load_lds_dwordx4 v162, s[36:37]
	s_mov_b32 m0, s40
	s_nop 0
	global_load_lds_dwordx4 v158, s[36:37]
	s_waitcnt vmcnt(8)
	s_waitcnt lgkmcnt(0)
	s_barrier
; #define PG8_STAGE(bufoff, gbase, voff) do { _Pragma("unroll") for (int _i = 0; _i < 2; ++_i) \
;         __builtin_amdgcn_global_load_lds((const unsigned*)((const char*)(gbase) + (voff)[_i]), (LAS unsigned*)(lds + (bufoff) + ldsw + _i * 8192), 16, 0, 0); } while (0)
; #define PG8_LDA(dst, b, h) do { _Pragma("unroll") for (int m = 0; m < 4; ++m) _Pragma("unroll") for (int k = 0; k < 2; ++k) dst[m][k] = *(const LAS bf16x8*)(lds + PG8_SA(b, h) + aoff + m * 2048 + k * 1024); } while (0)
; #define PG8_LDB(dst, b, h) do { _Pragma("unroll") for (int n = 0; n < 2; ++n) _Pragma("unroll") for (int k = 0; k < 2; ++k) dst[n][k] = *(const LAS bf16x8*)(lds + PG8_SB(b, h) + boff + n * 2048 + k * 1024); } while (0)
; #define PG8_MMA(ai, bj, At, Bt) do { __builtin_amdgcn_s_setprio(1); _Pragma("unroll") for (int m = 0; m < 4; ++m) _Pragma("unroll") for (int n = 0; n < 2; ++n) _Pragma("unroll") for (int k = 0; k < 2; ++k) \
;         acc[ai][bj][m][n] = __builtin_amdgcn_mfma_f32_16x16x32_bf16(Bt[n][k], At[m][k], acc[ai][bj][m][n], 0, 0, 0); __builtin_amdgcn_s_setprio(0); } while (0)
; #define PG8_WAIT_V(n) asm volatile("s_waitcnt vmcnt(" #n ")" ::: "memory")
; #define PG8_WAIT_L(n) asm volatile("s_waitcnt lgkmcnt(" #n ")" ::: "memory")
; #define PG8_BAR __builtin_amdgcn_s_barrier()
; #define PG8_SCHED __builtin_amdgcn_sched_barrier(0)
; template <class Epi, class Sched>
; __device__ __forceinline__ void gemm_phase(LAS unsigned char* lds, const Gemm g, const Sched& S, const Epi& E) {
;     ...
;             PG8_WAIT_V(8); PG8_WAIT_L(0); PG8_BAR; PG8_MMA(1, 0, At, B0); PG8_MMA(1, 1, At, B1); PG8_BAR; PG8_SCHED;
;             PG8_LDB(B0, 1, 0); PG8_LDB(B1, 1, 1); PG8_SCHED; PG8_LDA(At, 1, 0); PG8_STAGE(PG8_SA(0, 1), a2 + hstepA, voffA);
;             PG8_WAIT_V(8); PG8_WAIT_L(0); PG8_BAR; PG8_MMA(0, 0, At, B0); PG8_MMA(0, 1, At, B1); PG8_BAR; PG8_SCHED;
	s_setprio 1
	s_waitcnt lgkmcnt(0)
	v_mfma_f32_16x16x32_bf16 v[60:63], v[128:131], v[172:175], 0
	v_mfma_f32_16x16x32_bf16 v[56:59], v[136:139], v[172:175], 0
	v_mfma_f32_16x16x32_bf16 v[48:51], v[128:131], v[184:187], 0
	v_mfma_f32_16x16x32_bf16 v[40:43], v[136:139], v[184:187], 0
	v_mfma_f32_16x16x32_bf16 v[32:35], v[128:131], v[192:195], 0
	v_mfma_f32_16x16x32_bf16 v[24:27], v[136:139], v[192:195], 0
	v_mfma_f32_16x16x32_bf16 v[16:19], v[128:131], v[200:203], 0
	v_mfma_f32_16x16x32_bf16 v[8:11], v[136:139], v[200:203], 0
	v_mfma_f32_16x16x32_bf16 v[60:63], v[132:135], v[180:183], v[60:63]
	v_mfma_f32_16x16x32_bf16 v[56:59], v[140:143], v[180:183], v[56:59]
	v_mfma_f32_16x16x32_bf16 v[48:51], v[132:135], v[188:191], v[48:51]
	v_mfma_f32_16x16x32_bf16 v[40:43], v[140:143], v[188:191], v[40:43]
	v_mfma_f32_16x16x32_bf16 v[32:35], v[132:135], v[196:199], v[32:35]
	v_mfma_f32_16x16x32_bf16 v[24:27], v[140:143], v[196:199], v[24:27]
	v_mfma_f32_16x16x32_bf16 v[16:19], v[132:135], v[204:207], v[16:19]
	v_mfma_f32_16x16x32_bf16 v[8:11], v[140:143], v[204:207], v[8:11]
	s_setprio 0
	s_setprio 1
	v_mfma_f32_16x16x32_bf16 v[52:55], v[144:147], v[172:175], 0
	v_mfma_f32_16x16x32_bf16 v[44:47], v[152:155], v[172:175], 0
	v_mfma_f32_16x16x32_bf16 v[36:39], v[144:147], v[184:187], 0
	v_mfma_f32_16x16x32_bf16 v[28:31], v[152:155], v[184:187], 0
	v_mfma_f32_16x16x32_bf16 v[20:23], v[144:147], v[192:195], 0
	v_mfma_f32_16x16x32_bf16 v[12:15], v[152:155], v[192:195], 0
	v_mfma_f32_16x16x32_bf16 v[4:7], v[144:147], v[200:203], 0
	v_mfma_f32_16x16x32_bf16 v[0:3], v[152:155], v[200:203], 0
	v_mfma_f32_16x16x32_bf16 v[52:55], v[148:151], v[180:183], v[52:55]
	v_mfma_f32_16x16x32_bf16 v[44:47], v[168:171], v[180:183], v[44:47]
	v_mfma_f32_16x16x32_bf16 v[36:39], v[148:151], v[188:191], v[36:39]
	v_mfma_f32_16x16x32_bf16 v[28:31], v[168:171], v[188:191], v[28:31]
	v_mfma_f32_16x16x32_bf16 v[20:23], v[148:151], v[196:199], v[20:23]
	v_mfma_f32_16x16x32_bf16 v[12:15], v[168:171], v[196:199], v[12:15]
	v_mfma_f32_16x16x32_bf16 v[4:7], v[148:151], v[204:207], v[4:7]
	v_mfma_f32_16x16x32_bf16 v[0:3], v[168:171], v[204:207], v[0:3]
	s_setprio 0
	s_barrier
	s_add_i32 s52, 0, 0x18000
	s_add_i32 s53, 0, 0x1c000
	v_add_u32_e32 v140, s52, v178
	v_add_u32_e32 v168, s53, v178
	ds_read_b128 v[128:131], v140
	ds_read_b128 v[132:135], v140 offset:1024
	ds_read_b128 v[136:139], v140 offset:2048
	ds_read_b128 v[140:143], v140 offset:3072
	ds_read_b128 v[144:147], v168
	ds_read_b128 v[148:151], v168 offset:1024
	ds_read_b128 v[152:155], v168 offset:2048
	ds_read_b128 v[168:171], v168 offset:3072
	s_add_u32 s36, s36, 0x40000
	s_addc_u32 s37, s37, 0
	s_mov_b32 m0, s41
	ds_read_b128 v[172:175], v179 offset:32768
	ds_read_b128 v[180:183], v179 offset:33792
	ds_read_b128 v[184:187], v179 offset:34816
	ds_read_b128 v[188:191], v179 offset:35840
	ds_read_b128 v[192:195], v179 offset:36864
	ds_read_b128 v[196:199], v179 offset:37888
	ds_read_b128 v[200:203], v179 offset:38912
	ds_read_b128 v[204:207], v179 offset:39936
	global_load_lds_dwordx4 v162, s[36:37]
	s_mov_b32 m0, s42
	s_nop 0
	global_load_lds_dwordx4 v158, s[36:37]
	s_waitcnt vmcnt(8)
	s_waitcnt lgkmcnt(0)
	s_barrier
	s_setprio 1
	s_waitcnt lgkmcnt(0)
	v_mfma_f32_16x16x32_bf16 v[124:127], v[128:131], v[172:175], v[124:127]
	v_mfma_f32_16x16x32_bf16 v[120:123], v[136:139], v[172:175], v[120:123]
	v_mfma_f32_16x16x32_bf16 v[112:115], v[128:131], v[184:187], v[112:115]
	v_mfma_f32_16x16x32_bf16 v[104:107], v[136:139], v[184:187], v[104:107]
	v_mfma_f32_16x16x32_bf16 v[96:99], v[128:131], v[192:195], v[96:99]
	v_mfma_f32_16x16x32_bf16 v[88:91], v[136:139], v[192:195], v[88:91]
	v_mfma_f32_16x16x32_bf16 v[80:83], v[128:131], v[200:203], v[80:83]
	v_mfma_f32_16x16x32_bf16 v[72:75], v[136:139], v[200:203], v[72:75]
	v_mfma_f32_16x16x32_bf16 v[124:127], v[132:135], v[180:183], v[124:127]
	v_mfma_f32_16x16x32_bf16 v[120:123], v[140:143], v[180:183], v[120:123]
	v_mfma_f32_16x16x32_bf16 v[112:115], v[132:135], v[188:191], v[112:115]
	v_mfma_f32_16x16x32_bf16 v[104:107], v[140:143], v[188:191], v[104:107]
	v_mfma_f32_16x16x32_bf16 v[96:99], v[132:135], v[196:199], v[96:99]
	v_mfma_f32_16x16x32_bf16 v[88:91], v[140:143], v[196:199], v[88:91]
	v_mfma_f32_16x16x32_bf16 v[80:83], v[132:135], v[204:207], v[80:83]
	v_mfma_f32_16x16x32_bf16 v[72:75], v[140:143], v[204:207], v[72:75]
	s_setprio 0
	s_setprio 1
	v_mfma_f32_16x16x32_bf16 v[116:119], v[144:147], v[172:175], v[116:119]
	v_mfma_f32_16x16x32_bf16 v[108:111], v[152:155], v[172:175], v[108:111]
	v_mfma_f32_16x16x32_bf16 v[100:103], v[144:147], v[184:187], v[100:103]
	v_mfma_f32_16x16x32_bf16 v[92:95], v[152:155], v[184:187], v[92:95]
	v_mfma_f32_16x16x32_bf16 v[84:87], v[144:147], v[192:195], v[84:87]
	v_mfma_f32_16x16x32_bf16 v[76:79], v[152:155], v[192:195], v[76:79]
	v_mfma_f32_16x16x32_bf16 v[68:71], v[144:147], v[200:203], v[68:71]
	v_mfma_f32_16x16x32_bf16 v[64:67], v[152:155], v[200:203], v[64:67]
	v_mfma_f32_16x16x32_bf16 v[116:119], v[148:151], v[180:183], v[116:119]
	v_mfma_f32_16x16x32_bf16 v[108:111], v[168:171], v[180:183], v[108:111]
	v_mfma_f32_16x16x32_bf16 v[100:103], v[148:151], v[188:191], v[100:103]
	v_mfma_f32_16x16x32_bf16 v[92:95], v[168:171], v[188:191], v[92:95]
	v_mfma_f32_16x16x32_bf16 v[84:87], v[148:151], v[196:199], v[84:87]
	v_mfma_f32_16x16x32_bf16 v[76:79], v[168:171], v[196:199], v[76:79]
	v_mfma_f32_16x16x32_bf16 v[68:71], v[148:151], v[204:207], v[68:71]
	v_mfma_f32_16x16x32_bf16 v[64:67], v[168:171], v[204:207], v[64:67]
	s_setprio 0
	s_barrier
; #define PG8_STAGE(bufoff, gbase, voff) do { _Pragma("unroll") for (int _i = 0; _i < 2; ++_i) \
;         __builtin_amdgcn_global_load_lds((const unsigned*)((const char*)(gbase) + (voff)[_i]), (LAS unsigned*)(lds + (bufoff) + ldsw + _i * 8192), 16, 0, 0); } while (0)
; #define PG8_LDA(dst, b, h) do { _Pragma("unroll") for (int m = 0; m < 4; ++m) _Pragma("unroll") for (int k = 0; k < 2; ++k) dst[m][k] = *(const LAS bf16x8*)(lds + PG8_SA(b, h) + aoff + m * 2048 + k * 1024); } while (0)
; #define PG8_MMA(ai, bj, At, Bt) do { __builtin_amdgcn_s_setprio(1); _Pragma("unroll") for (int m = 0; m < 4; ++m) _Pragma("unroll") for (int n = 0; n < 2; ++n) _Pragma("unroll") for (int k = 0; k < 2; ++k) \
;         acc[ai][bj][m][n] = __builtin_amdgcn_mfma_f32_16x16x32_bf16(Bt[n][k], At[m][k], acc[ai][bj][m][n], 0, 0, 0); __builtin_amdgcn_s_setprio(0); } while (0)
; #define PG8_WAIT_V(n) asm volatile("s_waitcnt vmcnt(" #n ")" ::: "memory")
; #define PG8_WAIT_L(n) asm volatile("s_waitcnt lgkmcnt(" #n ")" ::: "memory")
; #define PG8_BAR __builtin_amdgcn_s_barrier()
; #define PG8_SCHED __builtin_amdgcn_sched_barrier(0)
; template <class Epi, class Sched>
; __device__ __forceinline__ void gemm_phase(LAS unsigned char* lds, const Gemm g, const Sched& S, const Epi& E) {
;     ...
;             PG8_LDA(At, 1, 1); PG8_STAGE(PG8_SB(1, 0), b3, voffB); PG8_STAGE(PG8_SB(1, 1), b3 + hstepB, voffB); PG8_STAGE(PG8_SA(1, 0), a3, voffA);
;             PG8_WAIT_V(8); PG8_WAIT_L(0); PG8_BAR; PG8_MMA(1, 0, At, B0); PG8_MMA(1, 1, At, B1); PG8_BAR; PG8_SCHED;
;         }
	s_add_u32 s98, s36, 0xfffc0080
	s_addc_u32 s99, s37, -1
	s_add_u32 s62, s26, 0x80
	s_addc_u32 s63, s27, 0
	s_add_i32 s36, s52, s2
	s_mov_b32 m0, s36
	ds_read_b128 v[172:175], v179 offset:49152
	ds_read_b128 v[180:183], v179 offset:50176
	ds_read_b128 v[184:187], v179 offset:51200
	ds_read_b128 v[188:191], v179 offset:52224
	ds_read_b128 v[192:195], v179 offset:53248
	ds_read_b128 v[196:199], v179 offset:54272
	ds_read_b128 v[200:203], v179 offset:55296
	ds_read_b128 v[204:207], v179 offset:56320
	global_load_lds_dwordx4 v160, s[62:63]
	s_add_i32 m0, s36, 0x2000
	s_add_u32 s26, s26, 0x40080
	s_addc_u32 s27, s27, 0
	s_add_i32 s36, s53, s2
	global_load_lds_dwordx4 v156, s[62:63]
	s_mov_b32 m0, s36
	s_nop 0
	global_load_lds_dwordx4 v160, s[26:27]
	s_add_i32 m0, s36, 0x2000
	s_nop 0
	global_load_lds_dwordx4 v156, s[26:27]
	s_mov_b32 m0, s44
	s_nop 0
	global_load_lds_dwordx4 v162, s[98:99]
	s_mov_b32 m0, s45
	s_nop 0
	global_load_lds_dwordx4 v158, s[98:99]
	s_waitcnt vmcnt(8)
	s_waitcnt lgkmcnt(0)
	s_barrier
	s_setprio 1
	s_waitcnt lgkmcnt(0)
	v_mfma_f32_16x16x32_bf16 v[60:63], v[128:131], v[172:175], v[60:63]
	v_mfma_f32_16x16x32_bf16 v[56:59], v[136:139], v[172:175], v[56:59]
	v_mfma_f32_16x16x32_bf16 v[48:51], v[128:131], v[184:187], v[48:51]
	v_mfma_f32_16x16x32_bf16 v[40:43], v[136:139], v[184:187], v[40:43]
	v_mfma_f32_16x16x32_bf16 v[32:35], v[128:131], v[192:195], v[32:35]
	v_mfma_f32_16x16x32_bf16 v[24:27], v[136:139], v[192:195], v[24:27]
	v_mfma_f32_16x16x32_bf16 v[16:19], v[128:131], v[200:203], v[16:19]
	v_mfma_f32_16x16x32_bf16 v[8:11], v[136:139], v[200:203], v[8:11]
	v_mfma_f32_16x16x32_bf16 v[60:63], v[132:135], v[180:183], v[60:63]
	v_mfma_f32_16x16x32_bf16 v[56:59], v[140:143], v[180:183], v[56:59]
	v_mfma_f32_16x16x32_bf16 v[48:51], v[132:135], v[188:191], v[48:51]
	v_mfma_f32_16x16x32_bf16 v[40:43], v[140:143], v[188:191], v[40:43]
	v_mfma_f32_16x16x32_bf16 v[32:35], v[132:135], v[196:199], v[32:35]
	v_mfma_f32_16x16x32_bf16 v[24:27], v[140:143], v[196:199], v[24:27]
	v_mfma_f32_16x16x32_bf16 v[16:19], v[132:135], v[204:207], v[16:19]
	v_mfma_f32_16x16x32_bf16 v[8:11], v[140:143], v[204:207], v[8:11]
	s_setprio 0
	s_setprio 1
	v_mfma_f32_16x16x32_bf16 v[52:55], v[144:147], v[172:175], v[52:55]
	v_mfma_f32_16x16x32_bf16 v[44:47], v[152:155], v[172:175], v[44:47]
	v_mfma_f32_16x16x32_bf16 v[36:39], v[144:147], v[184:187], v[36:39]
	v_mfma_f32_16x16x32_bf16 v[28:31], v[152:155], v[184:187], v[28:31]
	v_mfma_f32_16x16x32_bf16 v[20:23], v[144:147], v[192:195], v[20:23]
	v_mfma_f32_16x16x32_bf16 v[12:15], v[152:155], v[192:195], v[12:15]
	v_mfma_f32_16x16x32_bf16 v[4:7], v[144:147], v[200:203], v[4:7]
	v_mfma_f32_16x16x32_bf16 v[0:3], v[152:155], v[200:203], v[0:3]
	v_mfma_f32_16x16x32_bf16 v[52:55], v[148:151], v[180:183], v[52:55]
	v_mfma_f32_16x16x32_bf16 v[44:47], v[168:171], v[180:183], v[44:47]
	v_mfma_f32_16x16x32_bf16 v[36:39], v[148:151], v[188:191], v[36:39]
	v_mfma_f32_16x16x32_bf16 v[28:31], v[168:171], v[188:191], v[28:31]
	v_mfma_f32_16x16x32_bf16 v[20:23], v[148:151], v[196:199], v[20:23]
	v_mfma_f32_16x16x32_bf16 v[12:15], v[168:171], v[196:199], v[12:15]
	v_mfma_f32_16x16x32_bf16 v[4:7], v[148:151], v[204:207], v[4:7]
	v_mfma_f32_16x16x32_bf16 v[0:3], v[168:171], v[204:207], v[0:3]
	s_setprio 0
	s_barrier
	s_add_i32 s51, s51, 2
	s_add_u32 s24, s24, 0x100
	s_addc_u32 s25, s25, 0
	s_add_u32 s49, s49, 0x100
	s_addc_u32 s50, s50, 0
